# P1 norm pass hand-scheduled: x rows 4 deep in flight, a/shift vectors loaded once per batch, DPP wave sums, counted waits
# speedup vs baseline: 1.0043x; 1.0009x over previous
.LBB0_441:
	s_waitcnt lgkmcnt(0)
	v_mbcnt_lo_u32_b32 v207, -1, 0
	v_mbcnt_hi_u32_b32 v207, -1, v207
	v_lshlrev_b32_e32 v208, 3, v207
	v_lshlrev_b32_e32 v207, 4, v207
	v_mov_b32_e32 v206, 0x358637bd
	s_mov_b32 s22, 0x3a800000
	v_readlane_b32 s5, v254, 14
	v_readlane_b32 s2, v254, 8
	v_readlane_b32 s3, v254, 9
	s_lshl_b32 s5, s5, 3
	s_add_i32 s5, s5, s69
	s_lshl_b32 s4, s78, 24
	s_add_u32 s0, s12, s4
	s_addc_u32 s1, s13, 0
	s_lshl_b32 s4, s5, 12
	s_add_u32 s0, s0, s4
	s_addc_u32 s1, s1, 0
	s_add_u32 s2, s2, 0x4000000
	s_addc_u32 s3, s3, 0
	s_lshl_b32 s4, s78, 23
	s_add_u32 s2, s2, s4
	s_addc_u32 s3, s3, 0
	s_lshl_b32 s4, s5, 11
	s_add_u32 s2, s2, s4
	s_addc_u32 s3, s3, 0
	s_mul_i32 s4, s78, 0x12000
	s_add_u32 s8, s64, s4
	s_addc_u32 s9, s65, 0
	global_load_dwordx4 v[178:181], v207, s[8:9]
	global_load_dwordx4 v[182:185], v207, s[8:9] offset:1024
	global_load_dwordx4 v[186:189], v207, s[8:9] offset:2048
	global_load_dwordx4 v[190:193], v207, s[8:9] offset:3072
	s_add_u32 s8, s8, 0x1000
	s_addc_u32 s9, s9, 0
	global_load_dwordx4 v[162:165], v207, s[8:9]
	global_load_dwordx4 v[166:169], v207, s[8:9] offset:1024
	global_load_dwordx4 v[170:173], v207, s[8:9] offset:2048
	global_load_dwordx4 v[174:177], v207, s[8:9] offset:3072
	s_add_u32 s8, s8, 0x8000
	s_addc_u32 s9, s9, 0
	global_load_dwordx4 v[238:241], v207, s[8:9]
	global_load_dwordx4 v[242:245], v207, s[8:9] offset:1024
	global_load_dwordx4 v[246:249], v207, s[8:9] offset:2048
	global_load_dwordx4 v[250:253], v207, s[8:9] offset:3072
	s_add_u32 s8, s8, 0x1000
	s_addc_u32 s9, s9, 0
	global_load_dwordx4 v[222:225], v207, s[8:9]
	global_load_dwordx4 v[226:229], v207, s[8:9] offset:1024
	global_load_dwordx4 v[230:233], v207, s[8:9] offset:2048
	global_load_dwordx4 v[234:237], v207, s[8:9] offset:3072
	global_load_dwordx4 v[98:101], v207, s[0:1]
	global_load_dwordx4 v[102:105], v207, s[0:1] offset:1024
	global_load_dwordx4 v[106:109], v207, s[0:1] offset:2048
	global_load_dwordx4 v[110:113], v207, s[0:1] offset:3072
	s_add_u32 s0, s0, 0x100000
	s_addc_u32 s1, s1, 0
	global_load_dwordx4 v[114:117], v207, s[0:1]
	global_load_dwordx4 v[118:121], v207, s[0:1] offset:1024
	global_load_dwordx4 v[122:125], v207, s[0:1] offset:2048
	global_load_dwordx4 v[126:129], v207, s[0:1] offset:3072
	s_add_u32 s0, s0, 0x100000
	s_addc_u32 s1, s1, 0
	global_load_dwordx4 v[130:133], v207, s[0:1]
	global_load_dwordx4 v[134:137], v207, s[0:1] offset:1024
	global_load_dwordx4 v[138:141], v207, s[0:1] offset:2048
	global_load_dwordx4 v[142:145], v207, s[0:1] offset:3072
	s_add_u32 s0, s0, 0x100000
	s_addc_u32 s1, s1, 0
	global_load_dwordx4 v[146:149], v207, s[0:1]
	global_load_dwordx4 v[150:153], v207, s[0:1] offset:1024
	global_load_dwordx4 v[154:157], v207, s[0:1] offset:2048
	global_load_dwordx4 v[158:161], v207, s[0:1] offset:3072
	s_add_u32 s0, s0, 0x100000
	s_addc_u32 s1, s1, 0
	s_waitcnt vmcnt(8)
	v_mul_f32_e32 v194, v98, v98
	v_mul_f32_e32 v195, v102, v102
	v_mul_f32_e32 v196, v106, v106
	v_mul_f32_e32 v197, v110, v110
	v_mul_f32_e32 v198, v114, v114
	v_mul_f32_e32 v199, v118, v118
	v_mul_f32_e32 v200, v122, v122
	v_mul_f32_e32 v201, v126, v126
	v_fmac_f32_e32 v194, v99, v99
	v_fmac_f32_e32 v195, v103, v103
	v_fmac_f32_e32 v196, v107, v107
	v_fmac_f32_e32 v197, v111, v111
	v_fmac_f32_e32 v198, v115, v115
	v_fmac_f32_e32 v199, v119, v119
	v_fmac_f32_e32 v200, v123, v123
	v_fmac_f32_e32 v201, v127, v127
	v_fmac_f32_e32 v194, v100, v100
	v_fmac_f32_e32 v195, v104, v104
	v_fmac_f32_e32 v196, v108, v108
	v_fmac_f32_e32 v197, v112, v112
	v_fmac_f32_e32 v198, v116, v116
	v_fmac_f32_e32 v199, v120, v120
	v_fmac_f32_e32 v200, v124, v124
	v_fmac_f32_e32 v201, v128, v128
	v_fmac_f32_e32 v194, v101, v101
	v_fmac_f32_e32 v195, v105, v105
	v_fmac_f32_e32 v196, v109, v109
	v_fmac_f32_e32 v197, v113, v113
	v_fmac_f32_e32 v198, v117, v117
	v_fmac_f32_e32 v199, v121, v121
	v_fmac_f32_e32 v200, v125, v125
	v_fmac_f32_e32 v201, v129, v129
	v_add_f32_e32 v194, v194, v195
	v_add_f32_e32 v196, v196, v197
	v_add_f32_e32 v198, v198, v199
	v_add_f32_e32 v200, v200, v201
	v_add_f32_e32 v202, v194, v196
	v_add_f32_e32 v203, v198, v200
	s_nop 0
	v_add_f32_dpp v202, v202, v202 quad_perm:[1,0,3,2] row_mask:0xf bank_mask:0xf
	v_add_f32_dpp v203, v203, v203 quad_perm:[1,0,3,2] row_mask:0xf bank_mask:0xf
	s_nop 0
	v_add_f32_dpp v202, v202, v202 quad_perm:[2,3,0,1] row_mask:0xf bank_mask:0xf
	v_add_f32_dpp v203, v203, v203 quad_perm:[2,3,0,1] row_mask:0xf bank_mask:0xf
	s_nop 0
	v_add_f32_dpp v202, v202, v202 row_half_mirror row_mask:0xf bank_mask:0xf
	v_add_f32_dpp v203, v203, v203 row_half_mirror row_mask:0xf bank_mask:0xf
	s_nop 0
	v_add_f32_dpp v202, v202, v202 row_mirror row_mask:0xf bank_mask:0xf
	v_add_f32_dpp v203, v203, v203 row_mirror row_mask:0xf bank_mask:0xf
	s_nop 0
	v_add_f32_dpp v202, v202, v202 row_bcast:15 row_mask:0xa bank_mask:0xf
	v_add_f32_dpp v203, v203, v203 row_bcast:15 row_mask:0xa bank_mask:0xf
	s_nop 0
	v_add_f32_dpp v202, v202, v202 row_bcast:31 row_mask:0xc bank_mask:0xf
	v_add_f32_dpp v203, v203, v203 row_bcast:31 row_mask:0xc bank_mask:0xf
	s_nop 0
	v_fma_f32 v202, v202, s22, v206
	v_fma_f32 v203, v203, s22, v206
	v_rsq_f32_e32 v202, v202
	v_rsq_f32_e32 v203, v203
	s_nop 0
	v_readlane_b32 s10, v202, 63
	v_readlane_b32 s11, v203, 63
	s_nop 1
	v_mul_f32_e32 v204, s10, v98
	v_fma_f32 v98, v204, v162, v178
	v_mul_f32_e32 v205, s10, v99
	v_fma_f32 v99, v205, v163, v179
	v_mul_f32_e32 v204, s10, v100
	v_fma_f32 v100, v204, v164, v180
	v_mul_f32_e32 v205, s10, v101
	v_fma_f32 v101, v205, v165, v181
	v_mul_f32_e32 v204, s10, v102
	v_fma_f32 v102, v204, v166, v182
	v_mul_f32_e32 v205, s10, v103
	v_fma_f32 v103, v205, v167, v183
	v_mul_f32_e32 v204, s10, v104
	v_fma_f32 v104, v204, v168, v184
	v_mul_f32_e32 v205, s10, v105
	v_fma_f32 v105, v205, v169, v185
	v_mul_f32_e32 v204, s10, v106
	v_fma_f32 v106, v204, v170, v186
	v_mul_f32_e32 v205, s10, v107
	v_fma_f32 v107, v205, v171, v187
	v_mul_f32_e32 v204, s10, v108
	v_fma_f32 v108, v204, v172, v188
	v_mul_f32_e32 v205, s10, v109
	v_fma_f32 v109, v205, v173, v189
	v_mul_f32_e32 v204, s10, v110
	v_fma_f32 v110, v204, v174, v190
	v_mul_f32_e32 v205, s10, v111
	v_fma_f32 v111, v205, v175, v191
	v_mul_f32_e32 v204, s10, v112
	v_fma_f32 v112, v204, v176, v192
	v_mul_f32_e32 v205, s10, v113
	v_fma_f32 v113, v205, v177, v193
	v_cvt_pk_bf16_f32 v214, v98, v99
	v_cvt_pk_bf16_f32 v215, v100, v101
	v_cvt_pk_bf16_f32 v216, v102, v103
	v_cvt_pk_bf16_f32 v217, v104, v105
	v_cvt_pk_bf16_f32 v218, v106, v107
	v_cvt_pk_bf16_f32 v219, v108, v109
	v_cvt_pk_bf16_f32 v220, v110, v111
	v_cvt_pk_bf16_f32 v221, v112, v113
	global_store_dwordx2 v208, v[214:215], s[2:3]
	global_store_dwordx2 v208, v[216:217], s[2:3] offset:512
	global_store_dwordx2 v208, v[218:219], s[2:3] offset:1024
	global_store_dwordx2 v208, v[220:221], s[2:3] offset:1536
	s_add_u32 s2, s2, 0x80000
	s_addc_u32 s3, s3, 0
	v_mul_f32_e32 v204, s11, v114
	v_fma_f32 v114, v204, v162, v178
	v_mul_f32_e32 v205, s11, v115
	v_fma_f32 v115, v205, v163, v179
	v_mul_f32_e32 v204, s11, v116
	v_fma_f32 v116, v204, v164, v180
	v_mul_f32_e32 v205, s11, v117
	v_fma_f32 v117, v205, v165, v181
	v_mul_f32_e32 v204, s11, v118
	v_fma_f32 v118, v204, v166, v182
	v_mul_f32_e32 v205, s11, v119
	v_fma_f32 v119, v205, v167, v183
	v_mul_f32_e32 v204, s11, v120
	v_fma_f32 v120, v204, v168, v184
	v_mul_f32_e32 v205, s11, v121
	v_fma_f32 v121, v205, v169, v185
	v_mul_f32_e32 v204, s11, v122
	v_fma_f32 v122, v204, v170, v186
	v_mul_f32_e32 v205, s11, v123
	v_fma_f32 v123, v205, v171, v187
	v_mul_f32_e32 v204, s11, v124
	v_fma_f32 v124, v204, v172, v188
	v_mul_f32_e32 v205, s11, v125
	v_fma_f32 v125, v205, v173, v189
	v_mul_f32_e32 v204, s11, v126
	v_fma_f32 v126, v204, v174, v190
	v_mul_f32_e32 v205, s11, v127
	v_fma_f32 v127, v205, v175, v191
	v_mul_f32_e32 v204, s11, v128
	v_fma_f32 v128, v204, v176, v192
	v_mul_f32_e32 v205, s11, v129
	v_fma_f32 v129, v205, v177, v193
	v_cvt_pk_bf16_f32 v40, v114, v115
	v_cvt_pk_bf16_f32 v41, v116, v117
	v_cvt_pk_bf16_f32 v42, v118, v119
	v_cvt_pk_bf16_f32 v43, v120, v121
	v_cvt_pk_bf16_f32 v44, v122, v123
	v_cvt_pk_bf16_f32 v45, v124, v125
	v_cvt_pk_bf16_f32 v46, v126, v127
	v_cvt_pk_bf16_f32 v47, v128, v129
	global_store_dwordx2 v208, v[40:41], s[2:3]
	global_store_dwordx2 v208, v[42:43], s[2:3] offset:512
	global_store_dwordx2 v208, v[44:45], s[2:3] offset:1024
	global_store_dwordx2 v208, v[46:47], s[2:3] offset:1536
	s_add_u32 s2, s2, 0x80000
	s_addc_u32 s3, s3, 0
	global_load_dwordx4 v[98:101], v207, s[0:1]
	global_load_dwordx4 v[102:105], v207, s[0:1] offset:1024
	global_load_dwordx4 v[106:109], v207, s[0:1] offset:2048
	global_load_dwordx4 v[110:113], v207, s[0:1] offset:3072
	s_add_u32 s0, s0, 0x100000
	s_addc_u32 s1, s1, 0
	global_load_dwordx4 v[114:117], v207, s[0:1]
	global_load_dwordx4 v[118:121], v207, s[0:1] offset:1024
	global_load_dwordx4 v[122:125], v207, s[0:1] offset:2048
	global_load_dwordx4 v[126:129], v207, s[0:1] offset:3072
	s_add_u32 s0, s0, 0x100000
	s_addc_u32 s1, s1, 0
	s_waitcnt vmcnt(16)
	v_mul_f32_e32 v194, v130, v130
	v_mul_f32_e32 v195, v134, v134
	v_mul_f32_e32 v196, v138, v138
	v_mul_f32_e32 v197, v142, v142
	v_mul_f32_e32 v198, v146, v146
	v_mul_f32_e32 v199, v150, v150
	v_mul_f32_e32 v200, v154, v154
	v_mul_f32_e32 v201, v158, v158
	v_fmac_f32_e32 v194, v131, v131
	v_fmac_f32_e32 v195, v135, v135
	v_fmac_f32_e32 v196, v139, v139
	v_fmac_f32_e32 v197, v143, v143
	v_fmac_f32_e32 v198, v147, v147
	v_fmac_f32_e32 v199, v151, v151
	v_fmac_f32_e32 v200, v155, v155
	v_fmac_f32_e32 v201, v159, v159
	v_fmac_f32_e32 v194, v132, v132
	v_fmac_f32_e32 v195, v136, v136
	v_fmac_f32_e32 v196, v140, v140
	v_fmac_f32_e32 v197, v144, v144
	v_fmac_f32_e32 v198, v148, v148
	v_fmac_f32_e32 v199, v152, v152
	v_fmac_f32_e32 v200, v156, v156
	v_fmac_f32_e32 v201, v160, v160
	v_fmac_f32_e32 v194, v133, v133
	v_fmac_f32_e32 v195, v137, v137
	v_fmac_f32_e32 v196, v141, v141
	v_fmac_f32_e32 v197, v145, v145
	v_fmac_f32_e32 v198, v149, v149
	v_fmac_f32_e32 v199, v153, v153
	v_fmac_f32_e32 v200, v157, v157
	v_fmac_f32_e32 v201, v161, v161
	v_add_f32_e32 v194, v194, v195
	v_add_f32_e32 v196, v196, v197
	v_add_f32_e32 v198, v198, v199
	v_add_f32_e32 v200, v200, v201
	v_add_f32_e32 v202, v194, v196
	v_add_f32_e32 v203, v198, v200
	s_nop 0
	v_add_f32_dpp v202, v202, v202 quad_perm:[1,0,3,2] row_mask:0xf bank_mask:0xf
	v_add_f32_dpp v203, v203, v203 quad_perm:[1,0,3,2] row_mask:0xf bank_mask:0xf
	s_nop 0
	v_add_f32_dpp v202, v202, v202 quad_perm:[2,3,0,1] row_mask:0xf bank_mask:0xf
	v_add_f32_dpp v203, v203, v203 quad_perm:[2,3,0,1] row_mask:0xf bank_mask:0xf
	s_nop 0
	v_add_f32_dpp v202, v202, v202 row_half_mirror row_mask:0xf bank_mask:0xf
	v_add_f32_dpp v203, v203, v203 row_half_mirror row_mask:0xf bank_mask:0xf
	s_nop 0
	v_add_f32_dpp v202, v202, v202 row_mirror row_mask:0xf bank_mask:0xf
	v_add_f32_dpp v203, v203, v203 row_mirror row_mask:0xf bank_mask:0xf
	s_nop 0
	v_add_f32_dpp v202, v202, v202 row_bcast:15 row_mask:0xa bank_mask:0xf
	v_add_f32_dpp v203, v203, v203 row_bcast:15 row_mask:0xa bank_mask:0xf
	s_nop 0
	v_add_f32_dpp v202, v202, v202 row_bcast:31 row_mask:0xc bank_mask:0xf
	v_add_f32_dpp v203, v203, v203 row_bcast:31 row_mask:0xc bank_mask:0xf
	s_nop 0
	v_fma_f32 v202, v202, s22, v206
	v_fma_f32 v203, v203, s22, v206
	v_rsq_f32_e32 v202, v202
	v_rsq_f32_e32 v203, v203
	s_nop 0
	v_readlane_b32 s10, v202, 63
	v_readlane_b32 s11, v203, 63
	s_nop 1
	v_mul_f32_e32 v204, s10, v130
	v_fma_f32 v130, v204, v162, v178
	v_mul_f32_e32 v205, s10, v131
	v_fma_f32 v131, v205, v163, v179
	v_mul_f32_e32 v204, s10, v132
	v_fma_f32 v132, v204, v164, v180
	v_mul_f32_e32 v205, s10, v133
	v_fma_f32 v133, v205, v165, v181
	v_mul_f32_e32 v204, s10, v134
	v_fma_f32 v134, v204, v166, v182
	v_mul_f32_e32 v205, s10, v135
	v_fma_f32 v135, v205, v167, v183
	v_mul_f32_e32 v204, s10, v136
	v_fma_f32 v136, v204, v168, v184
	v_mul_f32_e32 v205, s10, v137
	v_fma_f32 v137, v205, v169, v185
	v_mul_f32_e32 v204, s10, v138
	v_fma_f32 v138, v204, v170, v186
	v_mul_f32_e32 v205, s10, v139
	v_fma_f32 v139, v205, v171, v187
	v_mul_f32_e32 v204, s10, v140
	v_fma_f32 v140, v204, v172, v188
	v_mul_f32_e32 v205, s10, v141
	v_fma_f32 v141, v205, v173, v189
	v_mul_f32_e32 v204, s10, v142
	v_fma_f32 v142, v204, v174, v190
	v_mul_f32_e32 v205, s10, v143
	v_fma_f32 v143, v205, v175, v191
	v_mul_f32_e32 v204, s10, v144
	v_fma_f32 v144, v204, v176, v192
	v_mul_f32_e32 v205, s10, v145
	v_fma_f32 v145, v205, v177, v193
	v_cvt_pk_bf16_f32 v214, v130, v131
	v_cvt_pk_bf16_f32 v215, v132, v133
	v_cvt_pk_bf16_f32 v216, v134, v135
	v_cvt_pk_bf16_f32 v217, v136, v137
	v_cvt_pk_bf16_f32 v218, v138, v139
	v_cvt_pk_bf16_f32 v219, v140, v141
	v_cvt_pk_bf16_f32 v220, v142, v143
	v_cvt_pk_bf16_f32 v221, v144, v145
	global_store_dwordx2 v208, v[214:215], s[2:3]
	global_store_dwordx2 v208, v[216:217], s[2:3] offset:512
	global_store_dwordx2 v208, v[218:219], s[2:3] offset:1024
	global_store_dwordx2 v208, v[220:221], s[2:3] offset:1536
	s_add_u32 s2, s2, 0x80000
	s_addc_u32 s3, s3, 0
	v_mul_f32_e32 v204, s11, v146
	v_fma_f32 v146, v204, v162, v178
	v_mul_f32_e32 v205, s11, v147
	v_fma_f32 v147, v205, v163, v179
	v_mul_f32_e32 v204, s11, v148
	v_fma_f32 v148, v204, v164, v180
	v_mul_f32_e32 v205, s11, v149
	v_fma_f32 v149, v205, v165, v181
	v_mul_f32_e32 v204, s11, v150
	v_fma_f32 v150, v204, v166, v182
	v_mul_f32_e32 v205, s11, v151
	v_fma_f32 v151, v205, v167, v183
	v_mul_f32_e32 v204, s11, v152
	v_fma_f32 v152, v204, v168, v184
	v_mul_f32_e32 v205, s11, v153
	v_fma_f32 v153, v205, v169, v185
	v_mul_f32_e32 v204, s11, v154
	v_fma_f32 v154, v204, v170, v186
	v_mul_f32_e32 v205, s11, v155
	v_fma_f32 v155, v205, v171, v187
	v_mul_f32_e32 v204, s11, v156
	v_fma_f32 v156, v204, v172, v188
	v_mul_f32_e32 v205, s11, v157
	v_fma_f32 v157, v205, v173, v189
	v_mul_f32_e32 v204, s11, v158
	v_fma_f32 v158, v204, v174, v190
	v_mul_f32_e32 v205, s11, v159
	v_fma_f32 v159, v205, v175, v191
	v_mul_f32_e32 v204, s11, v160
	v_fma_f32 v160, v204, v176, v192
	v_mul_f32_e32 v205, s11, v161
	v_fma_f32 v161, v205, v177, v193
	v_cvt_pk_bf16_f32 v40, v146, v147
	v_cvt_pk_bf16_f32 v41, v148, v149
	v_cvt_pk_bf16_f32 v42, v150, v151
	v_cvt_pk_bf16_f32 v43, v152, v153
	v_cvt_pk_bf16_f32 v44, v154, v155
	v_cvt_pk_bf16_f32 v45, v156, v157
	v_cvt_pk_bf16_f32 v46, v158, v159
	v_cvt_pk_bf16_f32 v47, v160, v161
	global_store_dwordx2 v208, v[40:41], s[2:3]
	global_store_dwordx2 v208, v[42:43], s[2:3] offset:512
	global_store_dwordx2 v208, v[44:45], s[2:3] offset:1024
	global_store_dwordx2 v208, v[46:47], s[2:3] offset:1536
	s_add_u32 s2, s2, 0x80000
	s_addc_u32 s3, s3, 0
	global_load_dwordx4 v[130:133], v207, s[0:1]
	global_load_dwordx4 v[134:137], v207, s[0:1] offset:1024
	global_load_dwordx4 v[138:141], v207, s[0:1] offset:2048
	global_load_dwordx4 v[142:145], v207, s[0:1] offset:3072
	s_add_u32 s0, s0, 0x100000
	s_addc_u32 s1, s1, 0
	global_load_dwordx4 v[146:149], v207, s[0:1]
	global_load_dwordx4 v[150:153], v207, s[0:1] offset:1024
	global_load_dwordx4 v[154:157], v207, s[0:1] offset:2048
	global_load_dwordx4 v[158:161], v207, s[0:1] offset:3072
	s_add_u32 s0, s0, 0x100000
	s_addc_u32 s1, s1, 0
	s_waitcnt vmcnt(16)
	v_mul_f32_e32 v194, v98, v98
	v_mul_f32_e32 v195, v102, v102
	v_mul_f32_e32 v196, v106, v106
	v_mul_f32_e32 v197, v110, v110
	v_mul_f32_e32 v198, v114, v114
	v_mul_f32_e32 v199, v118, v118
	v_mul_f32_e32 v200, v122, v122
	v_mul_f32_e32 v201, v126, v126
	v_fmac_f32_e32 v194, v99, v99
	v_fmac_f32_e32 v195, v103, v103
	v_fmac_f32_e32 v196, v107, v107
	v_fmac_f32_e32 v197, v111, v111
	v_fmac_f32_e32 v198, v115, v115
	v_fmac_f32_e32 v199, v119, v119
	v_fmac_f32_e32 v200, v123, v123
	v_fmac_f32_e32 v201, v127, v127
	v_fmac_f32_e32 v194, v100, v100
	v_fmac_f32_e32 v195, v104, v104
	v_fmac_f32_e32 v196, v108, v108
	v_fmac_f32_e32 v197, v112, v112
	v_fmac_f32_e32 v198, v116, v116
	v_fmac_f32_e32 v199, v120, v120
	v_fmac_f32_e32 v200, v124, v124
	v_fmac_f32_e32 v201, v128, v128
	v_fmac_f32_e32 v194, v101, v101
	v_fmac_f32_e32 v195, v105, v105
	v_fmac_f32_e32 v196, v109, v109
	v_fmac_f32_e32 v197, v113, v113
	v_fmac_f32_e32 v198, v117, v117
	v_fmac_f32_e32 v199, v121, v121
	v_fmac_f32_e32 v200, v125, v125
	v_fmac_f32_e32 v201, v129, v129
	v_add_f32_e32 v194, v194, v195
	v_add_f32_e32 v196, v196, v197
	v_add_f32_e32 v198, v198, v199
	v_add_f32_e32 v200, v200, v201
	v_add_f32_e32 v202, v194, v196
	v_add_f32_e32 v203, v198, v200
	s_nop 0
	v_add_f32_dpp v202, v202, v202 quad_perm:[1,0,3,2] row_mask:0xf bank_mask:0xf
	v_add_f32_dpp v203, v203, v203 quad_perm:[1,0,3,2] row_mask:0xf bank_mask:0xf
	s_nop 0
	v_add_f32_dpp v202, v202, v202 quad_perm:[2,3,0,1] row_mask:0xf bank_mask:0xf
	v_add_f32_dpp v203, v203, v203 quad_perm:[2,3,0,1] row_mask:0xf bank_mask:0xf
	s_nop 0
	v_add_f32_dpp v202, v202, v202 row_half_mirror row_mask:0xf bank_mask:0xf
	v_add_f32_dpp v203, v203, v203 row_half_mirror row_mask:0xf bank_mask:0xf
	s_nop 0
	v_add_f32_dpp v202, v202, v202 row_mirror row_mask:0xf bank_mask:0xf
	v_add_f32_dpp v203, v203, v203 row_mirror row_mask:0xf bank_mask:0xf
	s_nop 0
	v_add_f32_dpp v202, v202, v202 row_bcast:15 row_mask:0xa bank_mask:0xf
	v_add_f32_dpp v203, v203, v203 row_bcast:15 row_mask:0xa bank_mask:0xf
	s_nop 0
	v_add_f32_dpp v202, v202, v202 row_bcast:31 row_mask:0xc bank_mask:0xf
	v_add_f32_dpp v203, v203, v203 row_bcast:31 row_mask:0xc bank_mask:0xf
	s_nop 0
	v_fma_f32 v202, v202, s22, v206
	v_fma_f32 v203, v203, s22, v206
	v_rsq_f32_e32 v202, v202
	v_rsq_f32_e32 v203, v203
	s_nop 0
	v_readlane_b32 s10, v202, 63
	v_readlane_b32 s11, v203, 63
	s_nop 1
	v_mul_f32_e32 v204, s10, v98
	v_fma_f32 v98, v204, v162, v178
	v_mul_f32_e32 v205, s10, v99
	v_fma_f32 v99, v205, v163, v179
	v_mul_f32_e32 v204, s10, v100
	v_fma_f32 v100, v204, v164, v180
	v_mul_f32_e32 v205, s10, v101
	v_fma_f32 v101, v205, v165, v181
	v_mul_f32_e32 v204, s10, v102
	v_fma_f32 v102, v204, v166, v182
	v_mul_f32_e32 v205, s10, v103
	v_fma_f32 v103, v205, v167, v183
	v_mul_f32_e32 v204, s10, v104
	v_fma_f32 v104, v204, v168, v184
	v_mul_f32_e32 v205, s10, v105
	v_fma_f32 v105, v205, v169, v185
	v_mul_f32_e32 v204, s10, v106
	v_fma_f32 v106, v204, v170, v186
	v_mul_f32_e32 v205, s10, v107
	v_fma_f32 v107, v205, v171, v187
	v_mul_f32_e32 v204, s10, v108
	v_fma_f32 v108, v204, v172, v188
	v_mul_f32_e32 v205, s10, v109
	v_fma_f32 v109, v205, v173, v189
	v_mul_f32_e32 v204, s10, v110
	v_fma_f32 v110, v204, v174, v190
	v_mul_f32_e32 v205, s10, v111
	v_fma_f32 v111, v205, v175, v191
	v_mul_f32_e32 v204, s10, v112
	v_fma_f32 v112, v204, v176, v192
	v_mul_f32_e32 v205, s10, v113
	v_fma_f32 v113, v205, v177, v193
	v_cvt_pk_bf16_f32 v214, v98, v99
	v_cvt_pk_bf16_f32 v215, v100, v101
	v_cvt_pk_bf16_f32 v216, v102, v103
	v_cvt_pk_bf16_f32 v217, v104, v105
	v_cvt_pk_bf16_f32 v218, v106, v107
	v_cvt_pk_bf16_f32 v219, v108, v109
	v_cvt_pk_bf16_f32 v220, v110, v111
	v_cvt_pk_bf16_f32 v221, v112, v113
	global_store_dwordx2 v208, v[214:215], s[2:3]
	global_store_dwordx2 v208, v[216:217], s[2:3] offset:512
	global_store_dwordx2 v208, v[218:219], s[2:3] offset:1024
	global_store_dwordx2 v208, v[220:221], s[2:3] offset:1536
	s_add_u32 s2, s2, 0x80000
	s_addc_u32 s3, s3, 0
	v_mul_f32_e32 v204, s11, v114
	v_fma_f32 v114, v204, v162, v178
	v_mul_f32_e32 v205, s11, v115
	v_fma_f32 v115, v205, v163, v179
	v_mul_f32_e32 v204, s11, v116
	v_fma_f32 v116, v204, v164, v180
	v_mul_f32_e32 v205, s11, v117
	v_fma_f32 v117, v205, v165, v181
	v_mul_f32_e32 v204, s11, v118
	v_fma_f32 v118, v204, v166, v182
	v_mul_f32_e32 v205, s11, v119
	v_fma_f32 v119, v205, v167, v183
	v_mul_f32_e32 v204, s11, v120
	v_fma_f32 v120, v204, v168, v184
	v_mul_f32_e32 v205, s11, v121
	v_fma_f32 v121, v205, v169, v185
	v_mul_f32_e32 v204, s11, v122
	v_fma_f32 v122, v204, v170, v186
	v_mul_f32_e32 v205, s11, v123
	v_fma_f32 v123, v205, v171, v187
	v_mul_f32_e32 v204, s11, v124
	v_fma_f32 v124, v204, v172, v188
	v_mul_f32_e32 v205, s11, v125
	v_fma_f32 v125, v205, v173, v189
	v_mul_f32_e32 v204, s11, v126
	v_fma_f32 v126, v204, v174, v190
	v_mul_f32_e32 v205, s11, v127
	v_fma_f32 v127, v205, v175, v191
	v_mul_f32_e32 v204, s11, v128
	v_fma_f32 v128, v204, v176, v192
	v_mul_f32_e32 v205, s11, v129
	v_fma_f32 v129, v205, v177, v193
	v_cvt_pk_bf16_f32 v40, v114, v115
	v_cvt_pk_bf16_f32 v41, v116, v117
	v_cvt_pk_bf16_f32 v42, v118, v119
	v_cvt_pk_bf16_f32 v43, v120, v121
	v_cvt_pk_bf16_f32 v44, v122, v123
	v_cvt_pk_bf16_f32 v45, v124, v125
	v_cvt_pk_bf16_f32 v46, v126, v127
	v_cvt_pk_bf16_f32 v47, v128, v129
	global_store_dwordx2 v208, v[40:41], s[2:3]
	global_store_dwordx2 v208, v[42:43], s[2:3] offset:512
	global_store_dwordx2 v208, v[44:45], s[2:3] offset:1024
	global_store_dwordx2 v208, v[46:47], s[2:3] offset:1536
	s_add_u32 s2, s2, 0x80000
	s_addc_u32 s3, s3, 0
	global_load_dwordx4 v[98:101], v207, s[0:1]
	global_load_dwordx4 v[102:105], v207, s[0:1] offset:1024
	global_load_dwordx4 v[106:109], v207, s[0:1] offset:2048
	global_load_dwordx4 v[110:113], v207, s[0:1] offset:3072
	s_add_u32 s0, s0, 0x100000
	s_addc_u32 s1, s1, 0
	global_load_dwordx4 v[114:117], v207, s[0:1]
	global_load_dwordx4 v[118:121], v207, s[0:1] offset:1024
	global_load_dwordx4 v[122:125], v207, s[0:1] offset:2048
	global_load_dwordx4 v[126:129], v207, s[0:1] offset:3072
	s_add_u32 s0, s0, 0x100000
	s_addc_u32 s1, s1, 0
	s_waitcnt vmcnt(16)
	v_mul_f32_e32 v194, v130, v130
	v_mul_f32_e32 v195, v134, v134
	v_mul_f32_e32 v196, v138, v138
	v_mul_f32_e32 v197, v142, v142
	v_mul_f32_e32 v198, v146, v146
	v_mul_f32_e32 v199, v150, v150
	v_mul_f32_e32 v200, v154, v154
	v_mul_f32_e32 v201, v158, v158
	v_fmac_f32_e32 v194, v131, v131
	v_fmac_f32_e32 v195, v135, v135
	v_fmac_f32_e32 v196, v139, v139
	v_fmac_f32_e32 v197, v143, v143
	v_fmac_f32_e32 v198, v147, v147
	v_fmac_f32_e32 v199, v151, v151
	v_fmac_f32_e32 v200, v155, v155
	v_fmac_f32_e32 v201, v159, v159
	v_fmac_f32_e32 v194, v132, v132
	v_fmac_f32_e32 v195, v136, v136
	v_fmac_f32_e32 v196, v140, v140
	v_fmac_f32_e32 v197, v144, v144
	v_fmac_f32_e32 v198, v148, v148
	v_fmac_f32_e32 v199, v152, v152
	v_fmac_f32_e32 v200, v156, v156
	v_fmac_f32_e32 v201, v160, v160
	v_fmac_f32_e32 v194, v133, v133
	v_fmac_f32_e32 v195, v137, v137
	v_fmac_f32_e32 v196, v141, v141
	v_fmac_f32_e32 v197, v145, v145
	v_fmac_f32_e32 v198, v149, v149
	v_fmac_f32_e32 v199, v153, v153
	v_fmac_f32_e32 v200, v157, v157
	v_fmac_f32_e32 v201, v161, v161
	v_add_f32_e32 v194, v194, v195
	v_add_f32_e32 v196, v196, v197
	v_add_f32_e32 v198, v198, v199
	v_add_f32_e32 v200, v200, v201
	v_add_f32_e32 v202, v194, v196
	v_add_f32_e32 v203, v198, v200
	s_nop 0
	v_add_f32_dpp v202, v202, v202 quad_perm:[1,0,3,2] row_mask:0xf bank_mask:0xf
	v_add_f32_dpp v203, v203, v203 quad_perm:[1,0,3,2] row_mask:0xf bank_mask:0xf
	s_nop 0
	v_add_f32_dpp v202, v202, v202 quad_perm:[2,3,0,1] row_mask:0xf bank_mask:0xf
	v_add_f32_dpp v203, v203, v203 quad_perm:[2,3,0,1] row_mask:0xf bank_mask:0xf
	s_nop 0
	v_add_f32_dpp v202, v202, v202 row_half_mirror row_mask:0xf bank_mask:0xf
	v_add_f32_dpp v203, v203, v203 row_half_mirror row_mask:0xf bank_mask:0xf
	s_nop 0
	v_add_f32_dpp v202, v202, v202 row_mirror row_mask:0xf bank_mask:0xf
	v_add_f32_dpp v203, v203, v203 row_mirror row_mask:0xf bank_mask:0xf
	s_nop 0
	v_add_f32_dpp v202, v202, v202 row_bcast:15 row_mask:0xa bank_mask:0xf
	v_add_f32_dpp v203, v203, v203 row_bcast:15 row_mask:0xa bank_mask:0xf
	s_nop 0
	v_add_f32_dpp v202, v202, v202 row_bcast:31 row_mask:0xc bank_mask:0xf
	v_add_f32_dpp v203, v203, v203 row_bcast:31 row_mask:0xc bank_mask:0xf
	s_nop 0
	v_fma_f32 v202, v202, s22, v206
	v_fma_f32 v203, v203, s22, v206
	v_rsq_f32_e32 v202, v202
	v_rsq_f32_e32 v203, v203
	s_nop 0
	v_readlane_b32 s10, v202, 63
	v_readlane_b32 s11, v203, 63
	s_nop 1
	v_mul_f32_e32 v204, s10, v130
	v_fma_f32 v130, v204, v162, v178
	v_mul_f32_e32 v205, s10, v131
	v_fma_f32 v131, v205, v163, v179
	v_mul_f32_e32 v204, s10, v132
	v_fma_f32 v132, v204, v164, v180
	v_mul_f32_e32 v205, s10, v133
	v_fma_f32 v133, v205, v165, v181
	v_mul_f32_e32 v204, s10, v134
	v_fma_f32 v134, v204, v166, v182
	v_mul_f32_e32 v205, s10, v135
	v_fma_f32 v135, v205, v167, v183
	v_mul_f32_e32 v204, s10, v136
	v_fma_f32 v136, v204, v168, v184
	v_mul_f32_e32 v205, s10, v137
	v_fma_f32 v137, v205, v169, v185
	v_mul_f32_e32 v204, s10, v138
	v_fma_f32 v138, v204, v170, v186
	v_mul_f32_e32 v205, s10, v139
	v_fma_f32 v139, v205, v171, v187
	v_mul_f32_e32 v204, s10, v140
	v_fma_f32 v140, v204, v172, v188
	v_mul_f32_e32 v205, s10, v141
	v_fma_f32 v141, v205, v173, v189
	v_mul_f32_e32 v204, s10, v142
	v_fma_f32 v142, v204, v174, v190
	v_mul_f32_e32 v205, s10, v143
	v_fma_f32 v143, v205, v175, v191
	v_mul_f32_e32 v204, s10, v144
	v_fma_f32 v144, v204, v176, v192
	v_mul_f32_e32 v205, s10, v145
	v_fma_f32 v145, v205, v177, v193
	v_cvt_pk_bf16_f32 v214, v130, v131
	v_cvt_pk_bf16_f32 v215, v132, v133
	v_cvt_pk_bf16_f32 v216, v134, v135
	v_cvt_pk_bf16_f32 v217, v136, v137
	v_cvt_pk_bf16_f32 v218, v138, v139
	v_cvt_pk_bf16_f32 v219, v140, v141
	v_cvt_pk_bf16_f32 v220, v142, v143
	v_cvt_pk_bf16_f32 v221, v144, v145
	global_store_dwordx2 v208, v[214:215], s[2:3]
	global_store_dwordx2 v208, v[216:217], s[2:3] offset:512
	global_store_dwordx2 v208, v[218:219], s[2:3] offset:1024
	global_store_dwordx2 v208, v[220:221], s[2:3] offset:1536
	s_add_u32 s2, s2, 0x80000
	s_addc_u32 s3, s3, 0
	v_mul_f32_e32 v204, s11, v146
	v_fma_f32 v146, v204, v162, v178
	v_mul_f32_e32 v205, s11, v147
	v_fma_f32 v147, v205, v163, v179
	v_mul_f32_e32 v204, s11, v148
	v_fma_f32 v148, v204, v164, v180
	v_mul_f32_e32 v205, s11, v149
	v_fma_f32 v149, v205, v165, v181
	v_mul_f32_e32 v204, s11, v150
	v_fma_f32 v150, v204, v166, v182
	v_mul_f32_e32 v205, s11, v151
	v_fma_f32 v151, v205, v167, v183
	v_mul_f32_e32 v204, s11, v152
	v_fma_f32 v152, v204, v168, v184
	v_mul_f32_e32 v205, s11, v153
	v_fma_f32 v153, v205, v169, v185
	v_mul_f32_e32 v204, s11, v154
	v_fma_f32 v154, v204, v170, v186
	v_mul_f32_e32 v205, s11, v155
	v_fma_f32 v155, v205, v171, v187
	v_mul_f32_e32 v204, s11, v156
	v_fma_f32 v156, v204, v172, v188
	v_mul_f32_e32 v205, s11, v157
	v_fma_f32 v157, v205, v173, v189
	v_mul_f32_e32 v204, s11, v158
	v_fma_f32 v158, v204, v174, v190
	v_mul_f32_e32 v205, s11, v159
	v_fma_f32 v159, v205, v175, v191
	v_mul_f32_e32 v204, s11, v160
	v_fma_f32 v160, v204, v176, v192
	v_mul_f32_e32 v205, s11, v161
	v_fma_f32 v161, v205, v177, v193
	v_cvt_pk_bf16_f32 v40, v146, v147
	v_cvt_pk_bf16_f32 v41, v148, v149
	v_cvt_pk_bf16_f32 v42, v150, v151
	v_cvt_pk_bf16_f32 v43, v152, v153
	v_cvt_pk_bf16_f32 v44, v154, v155
	v_cvt_pk_bf16_f32 v45, v156, v157
	v_cvt_pk_bf16_f32 v46, v158, v159
	v_cvt_pk_bf16_f32 v47, v160, v161
	global_store_dwordx2 v208, v[40:41], s[2:3]
	global_store_dwordx2 v208, v[42:43], s[2:3] offset:512
	global_store_dwordx2 v208, v[44:45], s[2:3] offset:1024
	global_store_dwordx2 v208, v[46:47], s[2:3] offset:1536
	s_add_u32 s2, s2, 0x80000
	s_addc_u32 s3, s3, 0
	global_load_dwordx4 v[130:133], v207, s[0:1]
	global_load_dwordx4 v[134:137], v207, s[0:1] offset:1024
	global_load_dwordx4 v[138:141], v207, s[0:1] offset:2048
	global_load_dwordx4 v[142:145], v207, s[0:1] offset:3072
	s_add_u32 s0, s0, 0x100000
	s_addc_u32 s1, s1, 0
	global_load_dwordx4 v[146:149], v207, s[0:1]
	global_load_dwordx4 v[150:153], v207, s[0:1] offset:1024
	global_load_dwordx4 v[154:157], v207, s[0:1] offset:2048
	global_load_dwordx4 v[158:161], v207, s[0:1] offset:3072
	s_add_u32 s0, s0, 0x100000
	s_addc_u32 s1, s1, 0
	s_waitcnt vmcnt(16)
	v_mul_f32_e32 v194, v98, v98
	v_mul_f32_e32 v195, v102, v102
	v_mul_f32_e32 v196, v106, v106
	v_mul_f32_e32 v197, v110, v110
	v_mul_f32_e32 v198, v114, v114
	v_mul_f32_e32 v199, v118, v118
	v_mul_f32_e32 v200, v122, v122
	v_mul_f32_e32 v201, v126, v126
	v_fmac_f32_e32 v194, v99, v99
	v_fmac_f32_e32 v195, v103, v103
	v_fmac_f32_e32 v196, v107, v107
	v_fmac_f32_e32 v197, v111, v111
	v_fmac_f32_e32 v198, v115, v115
	v_fmac_f32_e32 v199, v119, v119
	v_fmac_f32_e32 v200, v123, v123
	v_fmac_f32_e32 v201, v127, v127
	v_fmac_f32_e32 v194, v100, v100
	v_fmac_f32_e32 v195, v104, v104
	v_fmac_f32_e32 v196, v108, v108
	v_fmac_f32_e32 v197, v112, v112
	v_fmac_f32_e32 v198, v116, v116
	v_fmac_f32_e32 v199, v120, v120
	v_fmac_f32_e32 v200, v124, v124
	v_fmac_f32_e32 v201, v128, v128
	v_fmac_f32_e32 v194, v101, v101
	v_fmac_f32_e32 v195, v105, v105
	v_fmac_f32_e32 v196, v109, v109
	v_fmac_f32_e32 v197, v113, v113
	v_fmac_f32_e32 v198, v117, v117
	v_fmac_f32_e32 v199, v121, v121
	v_fmac_f32_e32 v200, v125, v125
	v_fmac_f32_e32 v201, v129, v129
	v_add_f32_e32 v194, v194, v195
	v_add_f32_e32 v196, v196, v197
	v_add_f32_e32 v198, v198, v199
	v_add_f32_e32 v200, v200, v201
	v_add_f32_e32 v202, v194, v196
	v_add_f32_e32 v203, v198, v200
	s_nop 0
	v_add_f32_dpp v202, v202, v202 quad_perm:[1,0,3,2] row_mask:0xf bank_mask:0xf
	v_add_f32_dpp v203, v203, v203 quad_perm:[1,0,3,2] row_mask:0xf bank_mask:0xf
	s_nop 0
	v_add_f32_dpp v202, v202, v202 quad_perm:[2,3,0,1] row_mask:0xf bank_mask:0xf
	v_add_f32_dpp v203, v203, v203 quad_perm:[2,3,0,1] row_mask:0xf bank_mask:0xf
	s_nop 0
	v_add_f32_dpp v202, v202, v202 row_half_mirror row_mask:0xf bank_mask:0xf
	v_add_f32_dpp v203, v203, v203 row_half_mirror row_mask:0xf bank_mask:0xf
	s_nop 0
	v_add_f32_dpp v202, v202, v202 row_mirror row_mask:0xf bank_mask:0xf
	v_add_f32_dpp v203, v203, v203 row_mirror row_mask:0xf bank_mask:0xf
	s_nop 0
	v_add_f32_dpp v202, v202, v202 row_bcast:15 row_mask:0xa bank_mask:0xf
	v_add_f32_dpp v203, v203, v203 row_bcast:15 row_mask:0xa bank_mask:0xf
	s_nop 0
	v_add_f32_dpp v202, v202, v202 row_bcast:31 row_mask:0xc bank_mask:0xf
	v_add_f32_dpp v203, v203, v203 row_bcast:31 row_mask:0xc bank_mask:0xf
	s_nop 0
	v_fma_f32 v202, v202, s22, v206
	v_fma_f32 v203, v203, s22, v206
	v_rsq_f32_e32 v202, v202
	v_rsq_f32_e32 v203, v203
	s_nop 0
	v_readlane_b32 s10, v202, 63
	v_readlane_b32 s11, v203, 63
	s_nop 1
	v_mul_f32_e32 v204, s10, v98
	v_fma_f32 v98, v204, v222, v238
	v_mul_f32_e32 v205, s10, v99
	v_fma_f32 v99, v205, v223, v239
	v_mul_f32_e32 v204, s10, v100
	v_fma_f32 v100, v204, v224, v240
	v_mul_f32_e32 v205, s10, v101
	v_fma_f32 v101, v205, v225, v241
	v_mul_f32_e32 v204, s10, v102
	v_fma_f32 v102, v204, v226, v242
	v_mul_f32_e32 v205, s10, v103
	v_fma_f32 v103, v205, v227, v243
	v_mul_f32_e32 v204, s10, v104
	v_fma_f32 v104, v204, v228, v244
	v_mul_f32_e32 v205, s10, v105
	v_fma_f32 v105, v205, v229, v245
	v_mul_f32_e32 v204, s10, v106
	v_fma_f32 v106, v204, v230, v246
	v_mul_f32_e32 v205, s10, v107
	v_fma_f32 v107, v205, v231, v247
	v_mul_f32_e32 v204, s10, v108
	v_fma_f32 v108, v204, v232, v248
	v_mul_f32_e32 v205, s10, v109
	v_fma_f32 v109, v205, v233, v249
	v_mul_f32_e32 v204, s10, v110
	v_fma_f32 v110, v204, v234, v250
	v_mul_f32_e32 v205, s10, v111
	v_fma_f32 v111, v205, v235, v251
	v_mul_f32_e32 v204, s10, v112
	v_fma_f32 v112, v204, v236, v252
	v_mul_f32_e32 v205, s10, v113
	v_fma_f32 v113, v205, v237, v253
	v_cvt_pk_bf16_f32 v214, v98, v99
	v_cvt_pk_bf16_f32 v215, v100, v101
	v_cvt_pk_bf16_f32 v216, v102, v103
	v_cvt_pk_bf16_f32 v217, v104, v105
	v_cvt_pk_bf16_f32 v218, v106, v107
	v_cvt_pk_bf16_f32 v219, v108, v109
	v_cvt_pk_bf16_f32 v220, v110, v111
	v_cvt_pk_bf16_f32 v221, v112, v113
	global_store_dwordx2 v208, v[214:215], s[2:3]
	global_store_dwordx2 v208, v[216:217], s[2:3] offset:512
	global_store_dwordx2 v208, v[218:219], s[2:3] offset:1024
	global_store_dwordx2 v208, v[220:221], s[2:3] offset:1536
	s_add_u32 s2, s2, 0x80000
	s_addc_u32 s3, s3, 0
	v_mul_f32_e32 v204, s11, v114
	v_fma_f32 v114, v204, v222, v238
	v_mul_f32_e32 v205, s11, v115
	v_fma_f32 v115, v205, v223, v239
	v_mul_f32_e32 v204, s11, v116
	v_fma_f32 v116, v204, v224, v240
	v_mul_f32_e32 v205, s11, v117
	v_fma_f32 v117, v205, v225, v241
	v_mul_f32_e32 v204, s11, v118
	v_fma_f32 v118, v204, v226, v242
	v_mul_f32_e32 v205, s11, v119
	v_fma_f32 v119, v205, v227, v243
	v_mul_f32_e32 v204, s11, v120
	v_fma_f32 v120, v204, v228, v244
	v_mul_f32_e32 v205, s11, v121
	v_fma_f32 v121, v205, v229, v245
	v_mul_f32_e32 v204, s11, v122
	v_fma_f32 v122, v204, v230, v246
	v_mul_f32_e32 v205, s11, v123
	v_fma_f32 v123, v205, v231, v247
	v_mul_f32_e32 v204, s11, v124
	v_fma_f32 v124, v204, v232, v248
	v_mul_f32_e32 v205, s11, v125
	v_fma_f32 v125, v205, v233, v249
	v_mul_f32_e32 v204, s11, v126
	v_fma_f32 v126, v204, v234, v250
	v_mul_f32_e32 v205, s11, v127
	v_fma_f32 v127, v205, v235, v251
	v_mul_f32_e32 v204, s11, v128
	v_fma_f32 v128, v204, v236, v252
	v_mul_f32_e32 v205, s11, v129
	v_fma_f32 v129, v205, v237, v253
	v_cvt_pk_bf16_f32 v40, v114, v115
	v_cvt_pk_bf16_f32 v41, v116, v117
	v_cvt_pk_bf16_f32 v42, v118, v119
	v_cvt_pk_bf16_f32 v43, v120, v121
	v_cvt_pk_bf16_f32 v44, v122, v123
	v_cvt_pk_bf16_f32 v45, v124, v125
	v_cvt_pk_bf16_f32 v46, v126, v127
	v_cvt_pk_bf16_f32 v47, v128, v129
	global_store_dwordx2 v208, v[40:41], s[2:3]
	global_store_dwordx2 v208, v[42:43], s[2:3] offset:512
	global_store_dwordx2 v208, v[44:45], s[2:3] offset:1024
	global_store_dwordx2 v208, v[46:47], s[2:3] offset:1536
	s_add_u32 s2, s2, 0x80000
	s_addc_u32 s3, s3, 0
	global_load_dwordx4 v[98:101], v207, s[0:1]
	global_load_dwordx4 v[102:105], v207, s[0:1] offset:1024
	global_load_dwordx4 v[106:109], v207, s[0:1] offset:2048
	global_load_dwordx4 v[110:113], v207, s[0:1] offset:3072
	s_add_u32 s0, s0, 0x100000
	s_addc_u32 s1, s1, 0
	global_load_dwordx4 v[114:117], v207, s[0:1]
	global_load_dwordx4 v[118:121], v207, s[0:1] offset:1024
	global_load_dwordx4 v[122:125], v207, s[0:1] offset:2048
	global_load_dwordx4 v[126:129], v207, s[0:1] offset:3072
	s_add_u32 s0, s0, 0x100000
	s_addc_u32 s1, s1, 0
	s_waitcnt vmcnt(16)
	v_mul_f32_e32 v194, v130, v130
	v_mul_f32_e32 v195, v134, v134
	v_mul_f32_e32 v196, v138, v138
	v_mul_f32_e32 v197, v142, v142
	v_mul_f32_e32 v198, v146, v146
	v_mul_f32_e32 v199, v150, v150
	v_mul_f32_e32 v200, v154, v154
	v_mul_f32_e32 v201, v158, v158
	v_fmac_f32_e32 v194, v131, v131
	v_fmac_f32_e32 v195, v135, v135
	v_fmac_f32_e32 v196, v139, v139
	v_fmac_f32_e32 v197, v143, v143
	v_fmac_f32_e32 v198, v147, v147
	v_fmac_f32_e32 v199, v151, v151
	v_fmac_f32_e32 v200, v155, v155
	v_fmac_f32_e32 v201, v159, v159
	v_fmac_f32_e32 v194, v132, v132
	v_fmac_f32_e32 v195, v136, v136
	v_fmac_f32_e32 v196, v140, v140
	v_fmac_f32_e32 v197, v144, v144
	v_fmac_f32_e32 v198, v148, v148
	v_fmac_f32_e32 v199, v152, v152
	v_fmac_f32_e32 v200, v156, v156
	v_fmac_f32_e32 v201, v160, v160
	v_fmac_f32_e32 v194, v133, v133
	v_fmac_f32_e32 v195, v137, v137
	v_fmac_f32_e32 v196, v141, v141
	v_fmac_f32_e32 v197, v145, v145
	v_fmac_f32_e32 v198, v149, v149
	v_fmac_f32_e32 v199, v153, v153
	v_fmac_f32_e32 v200, v157, v157
	v_fmac_f32_e32 v201, v161, v161
	v_add_f32_e32 v194, v194, v195
	v_add_f32_e32 v196, v196, v197
	v_add_f32_e32 v198, v198, v199
	v_add_f32_e32 v200, v200, v201
	v_add_f32_e32 v202, v194, v196
	v_add_f32_e32 v203, v198, v200
	s_nop 0
	v_add_f32_dpp v202, v202, v202 quad_perm:[1,0,3,2] row_mask:0xf bank_mask:0xf
	v_add_f32_dpp v203, v203, v203 quad_perm:[1,0,3,2] row_mask:0xf bank_mask:0xf
	s_nop 0
	v_add_f32_dpp v202, v202, v202 quad_perm:[2,3,0,1] row_mask:0xf bank_mask:0xf
	v_add_f32_dpp v203, v203, v203 quad_perm:[2,3,0,1] row_mask:0xf bank_mask:0xf
	s_nop 0
	v_add_f32_dpp v202, v202, v202 row_half_mirror row_mask:0xf bank_mask:0xf
	v_add_f32_dpp v203, v203, v203 row_half_mirror row_mask:0xf bank_mask:0xf
	s_nop 0
	v_add_f32_dpp v202, v202, v202 row_mirror row_mask:0xf bank_mask:0xf
	v_add_f32_dpp v203, v203, v203 row_mirror row_mask:0xf bank_mask:0xf
	s_nop 0
	v_add_f32_dpp v202, v202, v202 row_bcast:15 row_mask:0xa bank_mask:0xf
	v_add_f32_dpp v203, v203, v203 row_bcast:15 row_mask:0xa bank_mask:0xf
	s_nop 0
	v_add_f32_dpp v202, v202, v202 row_bcast:31 row_mask:0xc bank_mask:0xf
	v_add_f32_dpp v203, v203, v203 row_bcast:31 row_mask:0xc bank_mask:0xf
	s_nop 0
	v_fma_f32 v202, v202, s22, v206
	v_fma_f32 v203, v203, s22, v206
	v_rsq_f32_e32 v202, v202
	v_rsq_f32_e32 v203, v203
	s_nop 0
	v_readlane_b32 s10, v202, 63
	v_readlane_b32 s11, v203, 63
	s_nop 1
	v_mul_f32_e32 v204, s10, v130
	v_fma_f32 v130, v204, v222, v238
	v_mul_f32_e32 v205, s10, v131
	v_fma_f32 v131, v205, v223, v239
	v_mul_f32_e32 v204, s10, v132
	v_fma_f32 v132, v204, v224, v240
	v_mul_f32_e32 v205, s10, v133
	v_fma_f32 v133, v205, v225, v241
	v_mul_f32_e32 v204, s10, v134
	v_fma_f32 v134, v204, v226, v242
	v_mul_f32_e32 v205, s10, v135
	v_fma_f32 v135, v205, v227, v243
	v_mul_f32_e32 v204, s10, v136
	v_fma_f32 v136, v204, v228, v244
	v_mul_f32_e32 v205, s10, v137
	v_fma_f32 v137, v205, v229, v245
	v_mul_f32_e32 v204, s10, v138
	v_fma_f32 v138, v204, v230, v246
	v_mul_f32_e32 v205, s10, v139
	v_fma_f32 v139, v205, v231, v247
	v_mul_f32_e32 v204, s10, v140
	v_fma_f32 v140, v204, v232, v248
	v_mul_f32_e32 v205, s10, v141
	v_fma_f32 v141, v205, v233, v249
	v_mul_f32_e32 v204, s10, v142
	v_fma_f32 v142, v204, v234, v250
	v_mul_f32_e32 v205, s10, v143
	v_fma_f32 v143, v205, v235, v251
	v_mul_f32_e32 v204, s10, v144
	v_fma_f32 v144, v204, v236, v252
	v_mul_f32_e32 v205, s10, v145
	v_fma_f32 v145, v205, v237, v253
	v_cvt_pk_bf16_f32 v214, v130, v131
	v_cvt_pk_bf16_f32 v215, v132, v133
	v_cvt_pk_bf16_f32 v216, v134, v135
	v_cvt_pk_bf16_f32 v217, v136, v137
	v_cvt_pk_bf16_f32 v218, v138, v139
	v_cvt_pk_bf16_f32 v219, v140, v141
	v_cvt_pk_bf16_f32 v220, v142, v143
	v_cvt_pk_bf16_f32 v221, v144, v145
	global_store_dwordx2 v208, v[214:215], s[2:3]
	global_store_dwordx2 v208, v[216:217], s[2:3] offset:512
	global_store_dwordx2 v208, v[218:219], s[2:3] offset:1024
	global_store_dwordx2 v208, v[220:221], s[2:3] offset:1536
	s_add_u32 s2, s2, 0x80000
	s_addc_u32 s3, s3, 0
	v_mul_f32_e32 v204, s11, v146
	v_fma_f32 v146, v204, v222, v238
	v_mul_f32_e32 v205, s11, v147
	v_fma_f32 v147, v205, v223, v239
	v_mul_f32_e32 v204, s11, v148
	v_fma_f32 v148, v204, v224, v240
	v_mul_f32_e32 v205, s11, v149
	v_fma_f32 v149, v205, v225, v241
	v_mul_f32_e32 v204, s11, v150
	v_fma_f32 v150, v204, v226, v242
	v_mul_f32_e32 v205, s11, v151
	v_fma_f32 v151, v205, v227, v243
	v_mul_f32_e32 v204, s11, v152
	v_fma_f32 v152, v204, v228, v244
	v_mul_f32_e32 v205, s11, v153
	v_fma_f32 v153, v205, v229, v245
	v_mul_f32_e32 v204, s11, v154
	v_fma_f32 v154, v204, v230, v246
	v_mul_f32_e32 v205, s11, v155
	v_fma_f32 v155, v205, v231, v247
	v_mul_f32_e32 v204, s11, v156
	v_fma_f32 v156, v204, v232, v248
	v_mul_f32_e32 v205, s11, v157
	v_fma_f32 v157, v205, v233, v249
	v_mul_f32_e32 v204, s11, v158
	v_fma_f32 v158, v204, v234, v250
	v_mul_f32_e32 v205, s11, v159
	v_fma_f32 v159, v205, v235, v251
	v_mul_f32_e32 v204, s11, v160
	v_fma_f32 v160, v204, v236, v252
	v_mul_f32_e32 v205, s11, v161
	v_fma_f32 v161, v205, v237, v253
	v_cvt_pk_bf16_f32 v40, v146, v147
	v_cvt_pk_bf16_f32 v41, v148, v149
	v_cvt_pk_bf16_f32 v42, v150, v151
	v_cvt_pk_bf16_f32 v43, v152, v153
	v_cvt_pk_bf16_f32 v44, v154, v155
	v_cvt_pk_bf16_f32 v45, v156, v157
	v_cvt_pk_bf16_f32 v46, v158, v159
	v_cvt_pk_bf16_f32 v47, v160, v161
	global_store_dwordx2 v208, v[40:41], s[2:3]
	global_store_dwordx2 v208, v[42:43], s[2:3] offset:512
	global_store_dwordx2 v208, v[44:45], s[2:3] offset:1024
	global_store_dwordx2 v208, v[46:47], s[2:3] offset:1536
	s_add_u32 s2, s2, 0x80000
	s_addc_u32 s3, s3, 0
	global_load_dwordx4 v[130:133], v207, s[0:1]
	global_load_dwordx4 v[134:137], v207, s[0:1] offset:1024
	global_load_dwordx4 v[138:141], v207, s[0:1] offset:2048
	global_load_dwordx4 v[142:145], v207, s[0:1] offset:3072
	s_add_u32 s0, s0, 0x100000
	s_addc_u32 s1, s1, 0
	global_load_dwordx4 v[146:149], v207, s[0:1]
	global_load_dwordx4 v[150:153], v207, s[0:1] offset:1024
	global_load_dwordx4 v[154:157], v207, s[0:1] offset:2048
	global_load_dwordx4 v[158:161], v207, s[0:1] offset:3072
	s_add_u32 s0, s0, 0x100000
	s_addc_u32 s1, s1, 0
	s_waitcnt vmcnt(16)
	v_mul_f32_e32 v194, v98, v98
	v_mul_f32_e32 v195, v102, v102
	v_mul_f32_e32 v196, v106, v106
	v_mul_f32_e32 v197, v110, v110
	v_mul_f32_e32 v198, v114, v114
	v_mul_f32_e32 v199, v118, v118
	v_mul_f32_e32 v200, v122, v122
	v_mul_f32_e32 v201, v126, v126
	v_fmac_f32_e32 v194, v99, v99
	v_fmac_f32_e32 v195, v103, v103
	v_fmac_f32_e32 v196, v107, v107
	v_fmac_f32_e32 v197, v111, v111
	v_fmac_f32_e32 v198, v115, v115
	v_fmac_f32_e32 v199, v119, v119
	v_fmac_f32_e32 v200, v123, v123
	v_fmac_f32_e32 v201, v127, v127
	v_fmac_f32_e32 v194, v100, v100
	v_fmac_f32_e32 v195, v104, v104
	v_fmac_f32_e32 v196, v108, v108
	v_fmac_f32_e32 v197, v112, v112
	v_fmac_f32_e32 v198, v116, v116
	v_fmac_f32_e32 v199, v120, v120
	v_fmac_f32_e32 v200, v124, v124
	v_fmac_f32_e32 v201, v128, v128
	v_fmac_f32_e32 v194, v101, v101
	v_fmac_f32_e32 v195, v105, v105
	v_fmac_f32_e32 v196, v109, v109
	v_fmac_f32_e32 v197, v113, v113
	v_fmac_f32_e32 v198, v117, v117
	v_fmac_f32_e32 v199, v121, v121
	v_fmac_f32_e32 v200, v125, v125
	v_fmac_f32_e32 v201, v129, v129
	v_add_f32_e32 v194, v194, v195
	v_add_f32_e32 v196, v196, v197
	v_add_f32_e32 v198, v198, v199
	v_add_f32_e32 v200, v200, v201
	v_add_f32_e32 v202, v194, v196
	v_add_f32_e32 v203, v198, v200
	s_nop 0
	v_add_f32_dpp v202, v202, v202 quad_perm:[1,0,3,2] row_mask:0xf bank_mask:0xf
	v_add_f32_dpp v203, v203, v203 quad_perm:[1,0,3,2] row_mask:0xf bank_mask:0xf
	s_nop 0
	v_add_f32_dpp v202, v202, v202 quad_perm:[2,3,0,1] row_mask:0xf bank_mask:0xf
	v_add_f32_dpp v203, v203, v203 quad_perm:[2,3,0,1] row_mask:0xf bank_mask:0xf
	s_nop 0
	v_add_f32_dpp v202, v202, v202 row_half_mirror row_mask:0xf bank_mask:0xf
	v_add_f32_dpp v203, v203, v203 row_half_mirror row_mask:0xf bank_mask:0xf
	s_nop 0
	v_add_f32_dpp v202, v202, v202 row_mirror row_mask:0xf bank_mask:0xf
	v_add_f32_dpp v203, v203, v203 row_mirror row_mask:0xf bank_mask:0xf
	s_nop 0
	v_add_f32_dpp v202, v202, v202 row_bcast:15 row_mask:0xa bank_mask:0xf
	v_add_f32_dpp v203, v203, v203 row_bcast:15 row_mask:0xa bank_mask:0xf
	s_nop 0
	v_add_f32_dpp v202, v202, v202 row_bcast:31 row_mask:0xc bank_mask:0xf
	v_add_f32_dpp v203, v203, v203 row_bcast:31 row_mask:0xc bank_mask:0xf
	s_nop 0
	v_fma_f32 v202, v202, s22, v206
	v_fma_f32 v203, v203, s22, v206
	v_rsq_f32_e32 v202, v202
	v_rsq_f32_e32 v203, v203
	s_nop 0
	v_readlane_b32 s10, v202, 63
	v_readlane_b32 s11, v203, 63
	s_nop 1
	v_mul_f32_e32 v204, s10, v98
	v_fma_f32 v98, v204, v222, v238
	v_mul_f32_e32 v205, s10, v99
	v_fma_f32 v99, v205, v223, v239
	v_mul_f32_e32 v204, s10, v100
	v_fma_f32 v100, v204, v224, v240
	v_mul_f32_e32 v205, s10, v101
	v_fma_f32 v101, v205, v225, v241
	v_mul_f32_e32 v204, s10, v102
	v_fma_f32 v102, v204, v226, v242
	v_mul_f32_e32 v205, s10, v103
	v_fma_f32 v103, v205, v227, v243
	v_mul_f32_e32 v204, s10, v104
	v_fma_f32 v104, v204, v228, v244
	v_mul_f32_e32 v205, s10, v105
	v_fma_f32 v105, v205, v229, v245
	v_mul_f32_e32 v204, s10, v106
	v_fma_f32 v106, v204, v230, v246
	v_mul_f32_e32 v205, s10, v107
	v_fma_f32 v107, v205, v231, v247
	v_mul_f32_e32 v204, s10, v108
	v_fma_f32 v108, v204, v232, v248
	v_mul_f32_e32 v205, s10, v109
	v_fma_f32 v109, v205, v233, v249
	v_mul_f32_e32 v204, s10, v110
	v_fma_f32 v110, v204, v234, v250
	v_mul_f32_e32 v205, s10, v111
	v_fma_f32 v111, v205, v235, v251
	v_mul_f32_e32 v204, s10, v112
	v_fma_f32 v112, v204, v236, v252
	v_mul_f32_e32 v205, s10, v113
	v_fma_f32 v113, v205, v237, v253
	v_cvt_pk_bf16_f32 v214, v98, v99
	v_cvt_pk_bf16_f32 v215, v100, v101
	v_cvt_pk_bf16_f32 v216, v102, v103
	v_cvt_pk_bf16_f32 v217, v104, v105
	v_cvt_pk_bf16_f32 v218, v106, v107
	v_cvt_pk_bf16_f32 v219, v108, v109
	v_cvt_pk_bf16_f32 v220, v110, v111
	v_cvt_pk_bf16_f32 v221, v112, v113
	global_store_dwordx2 v208, v[214:215], s[2:3]
	global_store_dwordx2 v208, v[216:217], s[2:3] offset:512
	global_store_dwordx2 v208, v[218:219], s[2:3] offset:1024
	global_store_dwordx2 v208, v[220:221], s[2:3] offset:1536
	s_add_u32 s2, s2, 0x80000
	s_addc_u32 s3, s3, 0
	v_mul_f32_e32 v204, s11, v114
	v_fma_f32 v114, v204, v222, v238
	v_mul_f32_e32 v205, s11, v115
	v_fma_f32 v115, v205, v223, v239
	v_mul_f32_e32 v204, s11, v116
	v_fma_f32 v116, v204, v224, v240
	v_mul_f32_e32 v205, s11, v117
	v_fma_f32 v117, v205, v225, v241
	v_mul_f32_e32 v204, s11, v118
	v_fma_f32 v118, v204, v226, v242
	v_mul_f32_e32 v205, s11, v119
	v_fma_f32 v119, v205, v227, v243
	v_mul_f32_e32 v204, s11, v120
	v_fma_f32 v120, v204, v228, v244
	v_mul_f32_e32 v205, s11, v121
	v_fma_f32 v121, v205, v229, v245
	v_mul_f32_e32 v204, s11, v122
	v_fma_f32 v122, v204, v230, v246
	v_mul_f32_e32 v205, s11, v123
	v_fma_f32 v123, v205, v231, v247
	v_mul_f32_e32 v204, s11, v124
	v_fma_f32 v124, v204, v232, v248
	v_mul_f32_e32 v205, s11, v125
	v_fma_f32 v125, v205, v233, v249
	v_mul_f32_e32 v204, s11, v126
	v_fma_f32 v126, v204, v234, v250
	v_mul_f32_e32 v205, s11, v127
	v_fma_f32 v127, v205, v235, v251
	v_mul_f32_e32 v204, s11, v128
	v_fma_f32 v128, v204, v236, v252
	v_mul_f32_e32 v205, s11, v129
	v_fma_f32 v129, v205, v237, v253
	v_cvt_pk_bf16_f32 v40, v114, v115
	v_cvt_pk_bf16_f32 v41, v116, v117
	v_cvt_pk_bf16_f32 v42, v118, v119
	v_cvt_pk_bf16_f32 v43, v120, v121
	v_cvt_pk_bf16_f32 v44, v122, v123
	v_cvt_pk_bf16_f32 v45, v124, v125
	v_cvt_pk_bf16_f32 v46, v126, v127
	v_cvt_pk_bf16_f32 v47, v128, v129
	global_store_dwordx2 v208, v[40:41], s[2:3]
	global_store_dwordx2 v208, v[42:43], s[2:3] offset:512
	global_store_dwordx2 v208, v[44:45], s[2:3] offset:1024
	global_store_dwordx2 v208, v[46:47], s[2:3] offset:1536
	s_add_u32 s2, s2, 0x80000
	s_addc_u32 s3, s3, 0
	s_waitcnt vmcnt(8)
	v_mul_f32_e32 v194, v130, v130
	v_mul_f32_e32 v195, v134, v134
	v_mul_f32_e32 v196, v138, v138
	v_mul_f32_e32 v197, v142, v142
	v_mul_f32_e32 v198, v146, v146
	v_mul_f32_e32 v199, v150, v150
	v_mul_f32_e32 v200, v154, v154
	v_mul_f32_e32 v201, v158, v158
	v_fmac_f32_e32 v194, v131, v131
	v_fmac_f32_e32 v195, v135, v135
	v_fmac_f32_e32 v196, v139, v139
	v_fmac_f32_e32 v197, v143, v143
	v_fmac_f32_e32 v198, v147, v147
	v_fmac_f32_e32 v199, v151, v151
	v_fmac_f32_e32 v200, v155, v155
	v_fmac_f32_e32 v201, v159, v159
	v_fmac_f32_e32 v194, v132, v132
	v_fmac_f32_e32 v195, v136, v136
	v_fmac_f32_e32 v196, v140, v140
	v_fmac_f32_e32 v197, v144, v144
	v_fmac_f32_e32 v198, v148, v148
	v_fmac_f32_e32 v199, v152, v152
	v_fmac_f32_e32 v200, v156, v156
	v_fmac_f32_e32 v201, v160, v160
	v_fmac_f32_e32 v194, v133, v133
	v_fmac_f32_e32 v195, v137, v137
	v_fmac_f32_e32 v196, v141, v141
	v_fmac_f32_e32 v197, v145, v145
	v_fmac_f32_e32 v198, v149, v149
	v_fmac_f32_e32 v199, v153, v153
	v_fmac_f32_e32 v200, v157, v157
	v_fmac_f32_e32 v201, v161, v161
	v_add_f32_e32 v194, v194, v195
	v_add_f32_e32 v196, v196, v197
	v_add_f32_e32 v198, v198, v199
	v_add_f32_e32 v200, v200, v201
	v_add_f32_e32 v202, v194, v196
	v_add_f32_e32 v203, v198, v200
	s_nop 0
	v_add_f32_dpp v202, v202, v202 quad_perm:[1,0,3,2] row_mask:0xf bank_mask:0xf
	v_add_f32_dpp v203, v203, v203 quad_perm:[1,0,3,2] row_mask:0xf bank_mask:0xf
	s_nop 0
	v_add_f32_dpp v202, v202, v202 quad_perm:[2,3,0,1] row_mask:0xf bank_mask:0xf
	v_add_f32_dpp v203, v203, v203 quad_perm:[2,3,0,1] row_mask:0xf bank_mask:0xf
	s_nop 0
	v_add_f32_dpp v202, v202, v202 row_half_mirror row_mask:0xf bank_mask:0xf
	v_add_f32_dpp v203, v203, v203 row_half_mirror row_mask:0xf bank_mask:0xf
	s_nop 0
	v_add_f32_dpp v202, v202, v202 row_mirror row_mask:0xf bank_mask:0xf
	v_add_f32_dpp v203, v203, v203 row_mirror row_mask:0xf bank_mask:0xf
	s_nop 0
	v_add_f32_dpp v202, v202, v202 row_bcast:15 row_mask:0xa bank_mask:0xf
	v_add_f32_dpp v203, v203, v203 row_bcast:15 row_mask:0xa bank_mask:0xf
	s_nop 0
	v_add_f32_dpp v202, v202, v202 row_bcast:31 row_mask:0xc bank_mask:0xf
	v_add_f32_dpp v203, v203, v203 row_bcast:31 row_mask:0xc bank_mask:0xf
	s_nop 0
	v_fma_f32 v202, v202, s22, v206
	v_fma_f32 v203, v203, s22, v206
	v_rsq_f32_e32 v202, v202
	v_rsq_f32_e32 v203, v203
	s_nop 0
	v_readlane_b32 s10, v202, 63
	v_readlane_b32 s11, v203, 63
	s_nop 1
	v_mul_f32_e32 v204, s10, v130
	v_fma_f32 v130, v204, v222, v238
	v_mul_f32_e32 v205, s10, v131
	v_fma_f32 v131, v205, v223, v239
	v_mul_f32_e32 v204, s10, v132
	v_fma_f32 v132, v204, v224, v240
	v_mul_f32_e32 v205, s10, v133
	v_fma_f32 v133, v205, v225, v241
	v_mul_f32_e32 v204, s10, v134
	v_fma_f32 v134, v204, v226, v242
	v_mul_f32_e32 v205, s10, v135
	v_fma_f32 v135, v205, v227, v243
	v_mul_f32_e32 v204, s10, v136
	v_fma_f32 v136, v204, v228, v244
	v_mul_f32_e32 v205, s10, v137
	v_fma_f32 v137, v205, v229, v245
	v_mul_f32_e32 v204, s10, v138
	v_fma_f32 v138, v204, v230, v246
	v_mul_f32_e32 v205, s10, v139
	v_fma_f32 v139, v205, v231, v247
	v_mul_f32_e32 v204, s10, v140
	v_fma_f32 v140, v204, v232, v248
	v_mul_f32_e32 v205, s10, v141
	v_fma_f32 v141, v205, v233, v249
	v_mul_f32_e32 v204, s10, v142
	v_fma_f32 v142, v204, v234, v250
	v_mul_f32_e32 v205, s10, v143
	v_fma_f32 v143, v205, v235, v251
	v_mul_f32_e32 v204, s10, v144
	v_fma_f32 v144, v204, v236, v252
	v_mul_f32_e32 v205, s10, v145
	v_fma_f32 v145, v205, v237, v253
	v_cvt_pk_bf16_f32 v214, v130, v131
	v_cvt_pk_bf16_f32 v215, v132, v133
	v_cvt_pk_bf16_f32 v216, v134, v135
	v_cvt_pk_bf16_f32 v217, v136, v137
	v_cvt_pk_bf16_f32 v218, v138, v139
	v_cvt_pk_bf16_f32 v219, v140, v141
	v_cvt_pk_bf16_f32 v220, v142, v143
	v_cvt_pk_bf16_f32 v221, v144, v145
	global_store_dwordx2 v208, v[214:215], s[2:3]
	global_store_dwordx2 v208, v[216:217], s[2:3] offset:512
	global_store_dwordx2 v208, v[218:219], s[2:3] offset:1024
	global_store_dwordx2 v208, v[220:221], s[2:3] offset:1536
	s_add_u32 s2, s2, 0x80000
	s_addc_u32 s3, s3, 0
	v_mul_f32_e32 v204, s11, v146
	v_fma_f32 v146, v204, v222, v238
	v_mul_f32_e32 v205, s11, v147
	v_fma_f32 v147, v205, v223, v239
	v_mul_f32_e32 v204, s11, v148
	v_fma_f32 v148, v204, v224, v240
	v_mul_f32_e32 v205, s11, v149
	v_fma_f32 v149, v205, v225, v241
	v_mul_f32_e32 v204, s11, v150
	v_fma_f32 v150, v204, v226, v242
	v_mul_f32_e32 v205, s11, v151
	v_fma_f32 v151, v205, v227, v243
	v_mul_f32_e32 v204, s11, v152
	v_fma_f32 v152, v204, v228, v244
	v_mul_f32_e32 v205, s11, v153
	v_fma_f32 v153, v205, v229, v245
	v_mul_f32_e32 v204, s11, v154
	v_fma_f32 v154, v204, v230, v246
	v_mul_f32_e32 v205, s11, v155
	v_fma_f32 v155, v205, v231, v247
	v_mul_f32_e32 v204, s11, v156
	v_fma_f32 v156, v204, v232, v248
	v_mul_f32_e32 v205, s11, v157
	v_fma_f32 v157, v205, v233, v249
	v_mul_f32_e32 v204, s11, v158
	v_fma_f32 v158, v204, v234, v250
	v_mul_f32_e32 v205, s11, v159
	v_fma_f32 v159, v205, v235, v251
	v_mul_f32_e32 v204, s11, v160
	v_fma_f32 v160, v204, v236, v252
	v_mul_f32_e32 v205, s11, v161
	v_fma_f32 v161, v205, v237, v253
	v_cvt_pk_bf16_f32 v40, v146, v147
	v_cvt_pk_bf16_f32 v41, v148, v149
	v_cvt_pk_bf16_f32 v42, v150, v151
	v_cvt_pk_bf16_f32 v43, v152, v153
	v_cvt_pk_bf16_f32 v44, v154, v155
	v_cvt_pk_bf16_f32 v45, v156, v157
	v_cvt_pk_bf16_f32 v46, v158, v159
	v_cvt_pk_bf16_f32 v47, v160, v161
	global_store_dwordx2 v208, v[40:41], s[2:3]
	global_store_dwordx2 v208, v[42:43], s[2:3] offset:512
	global_store_dwordx2 v208, v[44:45], s[2:3] offset:1024
	global_store_dwordx2 v208, v[46:47], s[2:3] offset:1536
	s_add_u32 s2, s2, 0x80000
	s_addc_u32 s3, s3, 0
	s_branch .LBB0_443
